# combine phase: per-row 16-lane sum of squares by four DPP adds instead of four ds_bpermute round trips
# speedup vs baseline: 1.0028x; 1.0028x over previous
; __device__ __forceinline__ unsigned pk2(float lo, float hi) { return f2bf(lo) | (f2bf(hi) << 16); }
; __global__ void __launch_bounds__(NWAVES * 64, 2) hymba_fwd(Args args) {
;     ...
;                 for (int mc = mc0; mc < M / 8; mc += mcs) { float wsum[8];
;                   for (int mr = 0; mr < 8; ++mr) { const int m = mc * 8 + mr;
;                     const v4u a = *(const v4u*)(OBUF + (size_t)m * 1024 + hd * 256 + j0), b = *(const v4u*)(OBUF + (size_t)m * 1024 + hd * 256 + 128 + j0);
;                     float o[8];
;                     o[0] = bflo(a.x) - lam * bflo(b.x); o[1] = bfhi(a.x) - lam * bfhi(b.x); o[2] = bflo(a.y) - lam * bflo(b.y); o[3] = bfhi(a.y) - lam * bfhi(b.y);
;                     o[4] = bflo(a.z) - lam * bflo(b.z); o[5] = bfhi(a.z) - lam * bfhi(b.z); o[6] = bflo(a.w) - lam * bflo(b.w); o[7] = bfhi(a.w) - lam * bfhi(b.w);
;                     float ss = 0.f;
; #pragma unroll
;                     for (int j = 0; j < 8; ++j) ss += o[j] * o[j];
;                     ss += __shfl_xor(ss, 1); ss += __shfl_xor(ss, 2); ss += __shfl_xor(ss, 4); ss += __shfl_xor(ss, 8);
;                     const float rr = __builtin_amdgcn_rsqf(ss * (1.0f / 128.0f) + 1e-6f);
;                     v4u w; w.x = pk2(o[0] * rr * gn[0], o[1] * rr * gn[1]); w.y = pk2(o[2] * rr * gn[2], o[3] * rr * gn[3]); w.z = pk2(o[4] * rr * gn[4], o[5] * rr * gn[5]); w.w = pk2(o[6] * rr * gn[6], o[7] * rr * gn[7]);
;                     *(v4u*)(CAT + (size_t)m * 1024 + hd * 128 + j0) = w;
;                     const bf16* up = QKVU + (size_t)m * 2112 + 1536 + hd * 128 + j0;
;                     const v4u u0 = *(const v4u*)up;
;                     const float us[8] = {bflo(u0.x), bfhi(u0.x), bflo(u0.y), bfhi(u0.y), bflo(u0.z), bfhi(u0.z), bflo(u0.w), bfhi(u0.w)};
;                     float sm[8];
;                     if (mr == 0) {
;                         v4u ut[15]; float wt[15];
; #pragma unroll
;                         for (int j = 0; j < 8; ++j) sm[j] = us[j];
; #pragma unroll
;                         for (int t = 1; t < 16; ++t) { const bool ok = (t < win) && (m - t >= 0); ut[t - 1] = *(const v4u*)(up - (size_t)(ok ? t : 0) * 2112); wt[t - 1] = ok ? 1.0f : 0.0f; }
; #pragma unroll
;                         for (int t = 0; t < 15; ++t) { const float w = wt[t];
.LBB0_438:
	s_add_i32 s86, s0, s41
	s_mov_b64 s[42:43], s[38:39]
	s_ashr_i32 s87, s86, 31
	s_lshl_b64 s[64:65], s[86:87], 11
	s_add_u32 s42, s42, s64
	s_addc_u32 s43, s43, s65
	v_lshl_add_u64 v[0:1], s[42:43], 0, v[42:43]
	v_lshlrev_b32_e32 v160, 1, v30
	v_lshl_add_u64 v[0:1], v[0:1], 0, v[160:161]
	v_add_co_u32_e32 v0, vcc, s96, v0
	s_mov_b64 s[42:43], s[38:39]
	s_nop 0
	v_addc_co_u32_e32 v1, vcc, 0, v1, vcc
	global_load_dwordx4 v[0:3], v[0:1], off
	s_add_u32 s42, s42, s64
	s_addc_u32 s43, s43, s65
	v_lshl_add_u64 v[4:5], s[42:43], 0, v[42:43]
	v_lshl_add_u64 v[4:5], v[4:5], 0, v[160:161]
	v_add_co_u32_e32 v4, vcc, s96, v4
	s_mov_b64 s[42:43], s[38:39]
	s_nop 0
	v_addc_co_u32_e32 v5, vcc, 0, v5, vcc
	global_load_dwordx4 v[4:7], v[4:5], off offset:256
	s_add_u32 s42, s42, s64
	s_addc_u32 s43, s43, s65
	s_mul_i32 s45, s86, 0x1080
	s_mul_hi_i32 s44, s86, 0x1080
	s_add_u32 s100, s38, s45
	s_addc_u32 s101, s39, s44
	v_cmp_lt_i32_e32 vcc, s86, v59
	v_lshlrev_b64 v[236:237], 1, v[40:41]
	v_lshl_add_u64 v[236:237], s[100:101], 0, v[236:237]
	v_lshl_add_u64 v[236:237], v[236:237], 0, v[160:161]
	s_mov_b64 s[100:101], 0x2800c00
	v_cndmask_b32_e64 v240, v59, 0, vcc
	v_lshl_add_u64 v[236:237], v[236:237], 0, s[100:101]
	v_mul_i32_i24_e32 v240, 0xffffef80, v240
	v_ashrrev_i32_e32 v241, 31, v240
	v_lshl_add_u64 v[240:241], v[236:237], 0, v[240:241]
	global_load_dwordx4 v[236:239], v[236:237], off
	global_load_dwordx4 v[240:243], v[240:241], off
	s_waitcnt vmcnt(3)
	v_lshlrev_b32_e32 v9, 16, v1
	v_lshlrev_b32_e32 v8, 16, v0
	v_and_b32_e32 v1, 0xffff0000, v1
	v_and_b32_e32 v0, 0xffff0000, v0
	v_lshlrev_b32_e32 v13, 16, v3
	v_lshlrev_b32_e32 v12, 16, v2
	v_and_b32_e32 v3, 0xffff0000, v3
	v_and_b32_e32 v2, 0xffff0000, v2
	s_waitcnt vmcnt(2)
	v_lshlrev_b32_e32 v11, 16, v5
	v_lshlrev_b32_e32 v10, 16, v4
	v_and_b32_e32 v5, 0xffff0000, v5
	v_and_b32_e32 v4, 0xffff0000, v4
	v_pk_fma_f32 v[8:9], v[28:29], v[10:11], v[8:9] neg_lo:[1,0,0] neg_hi:[1,0,0]
	v_pk_fma_f32 v[0:1], v[28:29], v[4:5], v[0:1] neg_lo:[1,0,0] neg_hi:[1,0,0]
	v_pk_mul_f32 v[4:5], v[8:9], v[8:9]
	v_pk_mul_f32 v[10:11], v[0:1], v[0:1]
	v_lshlrev_b32_e32 v15, 16, v7
	v_lshlrev_b32_e32 v14, 16, v6
	v_and_b32_e32 v7, 0xffff0000, v7
	v_and_b32_e32 v6, 0xffff0000, v6
	v_pk_fma_f32 v[12:13], v[28:29], v[14:15], v[12:13] neg_lo:[1,0,0] neg_hi:[1,0,0]
	v_pk_fma_f32 v[2:3], v[28:29], v[6:7], v[2:3] neg_lo:[1,0,0] neg_hi:[1,0,0]
	v_add_f32_e32 v4, v4, v10
	v_mov_b32_e32 v6, v12
	v_mov_b32_e32 v7, v2
	v_add_f32_e32 v4, v4, v5
	v_pk_mul_f32 v[6:7], v[6:7], v[6:7]
	v_add_f32_e32 v4, v4, v11
	v_mov_b32_e32 v14, v13
	v_mov_b32_e32 v15, v3
	v_add_f32_e32 v4, v4, v6
	v_pk_mul_f32 v[14:15], v[14:15], v[14:15]
	v_add_f32_e32 v4, v4, v7
	v_add_f32_e32 v4, v4, v14
	v_add_f32_e32 v4, v4, v15
	s_nop 1
	v_add_f32_dpp v4, v4, v4 quad_perm:[1,0,3,2] row_mask:0xf bank_mask:0xf
	s_nop 1
	v_add_f32_dpp v4, v4, v4 quad_perm:[2,3,0,1] row_mask:0xf bank_mask:0xf
	s_nop 1
	v_add_f32_dpp v4, v4, v4 row_half_mirror row_mask:0xf bank_mask:0xf
	s_nop 1
	v_add_f32_dpp v4, v4, v4 row_mirror row_mask:0xf bank_mask:0xf
	v_fmamk_f32 v4, v4, 0x3c000000, v225
	v_rsq_f32_e32 v4, v4
	s_nop 0
	v_pk_mul_f32 v[2:3], v[2:3], v[4:5] op_sel_hi:[1,0]
	v_pk_mul_f32 v[6:7], v[8:9], v[4:5] op_sel_hi:[1,0]
	v_pk_mul_f32 v[0:1], v[0:1], v[4:5] op_sel_hi:[1,0]
	v_pk_mul_f32 v[2:3], v[2:3], v[38:39]
	v_pk_mul_f32 v[6:7], v[32:33], v[6:7]
	v_pk_mul_f32 v[0:1], v[34:35], v[0:1]
	v_pk_mul_f32 v[8:9], v[12:13], v[4:5] op_sel_hi:[1,0]
	v_bfe_u32 v4, v3, 16, 1
	v_bfe_u32 v5, v2, 16, 1
	v_pk_mul_f32 v[8:9], v[8:9], v[36:37]
	v_bfe_u32 v10, v1, 16, 1
	v_bfe_u32 v11, v0, 16, 1
	v_add3_u32 v2, v2, v5, s97
	v_add3_u32 v3, v3, v4, s97
	v_bfe_u32 v4, v6, 16, 1
	v_bfe_u32 v5, v7, 16, 1
	v_add3_u32 v0, v0, v11, s97
	v_add3_u32 v1, v1, v10, s97
	v_bfe_u32 v10, v8, 16, 1
	v_bfe_u32 v11, v9, 16, 1
	v_add3_u32 v5, v7, v5, s97
	v_add3_u32 v4, v6, v4, s97
	v_add3_u32 v9, v9, v11, s97
	v_add3_u32 v8, v8, v10, s97
	v_lshrrev_b32_e32 v4, 16, v4
	v_lshrrev_b32_e32 v5, 16, v5
	v_lshrrev_b32_e32 v6, 16, v8
	v_lshrrev_b32_e32 v7, 16, v9
	v_and_or_b32 v1, v1, s94, v5
	v_and_or_b32 v0, v0, s94, v4
	v_lshlrev_b64 v[4:5], 1, v[40:41]
	v_and_or_b32 v3, v3, s94, v7
	v_and_or_b32 v2, v2, s94, v6
	v_lshl_add_u64 v[6:7], s[42:43], 0, v[4:5]
	v_lshl_add_u64 v[6:7], v[6:7], 0, v[160:161]
	s_mov_b32 s42, 0x8c00000
	v_add_co_u32_e32 v6, vcc, s42, v6
	s_mov_b64 s[42:43], s[38:39]
	s_nop 0
	v_addc_co_u32_e32 v7, vcc, 0, v7, vcc
	global_store_dwordx4 v[6:7], v[0:3], off
	s_add_u32 s42, s42, s45
	s_addc_u32 s43, s43, s44
	v_lshl_add_u64 v[0:1], s[42:43], 0, v[4:5]
	v_lshl_add_u64 v[0:1], v[0:1], 0, v[160:161]
	s_mov_b64 s[42:43], 0x2800c00
	v_lshl_add_u64 v[24:25], v[0:1], 0, s[42:43]
	s_mov_b32 s42, 0x2800000
	v_add_co_u32_e32 v0, vcc, s42, v0
	s_cmp_lg_u32 s41, 0
	s_nop 0
	v_addc_co_u32_e32 v1, vcc, 0, v1, vcc
	s_waitcnt vmcnt(2)
	v_lshlrev_b32_e32 v51, 16, v237
	v_lshlrev_b32_e32 v50, 16, v236
	v_and_b32_e32 v49, 0xffff0000, v237
	v_and_b32_e32 v48, 0xffff0000, v236
	v_lshlrev_b32_e32 v47, 16, v239
	v_lshlrev_b32_e32 v46, 16, v238
	v_and_b32_e32 v45, 0xffff0000, v239
	v_and_b32_e32 v44, 0xffff0000, v238
	s_cbranch_scc0 .LBB0_440
	v_cmp_lt_i32_e32 vcc, s86, v59
	s_movk_i32 s42, 0xef80
	v_mov_b32_e32 v4, v169
	v_cndmask_b32_e64 v0, v59, 0, vcc
	v_mad_i64_i32 v[0:1], s[42:43], v0, s42, v[24:25]
	v_mov_b32_e32 v169, v172
	v_mov_b32_e32 v8, v50
	v_mov_b32_e32 v9, v48
	v_cndmask_b32_e64 v6, 1.0, 0, vcc
	v_pk_add_f32 v[8:9], v[168:169], v[8:9]
	v_mov_b32_e32 v5, v173
	v_mov_b32_e32 v171, v174
	s_waitcnt vmcnt(1)
	v_lshlrev_b32_e32 v10, 16, v240
	v_and_b32_e32 v11, 0xffff0000, v240
	v_pk_fma_f32 v[8:9], v[6:7], v[10:11], v[8:9] op_sel_hi:[0,1,1] neg_lo:[1,0,0] neg_hi:[1,0,0]
	v_mov_b32_e32 v10, v51
	v_mov_b32_e32 v11, v49
	v_pk_add_f32 v[4:5], v[4:5], v[10:11]
	v_lshlrev_b32_e32 v0, 16, v241
	v_and_b32_e32 v1, 0xffff0000, v241
	v_pk_fma_f32 v[172:173], v[6:7], v[0:1], v[4:5] op_sel_hi:[0,1,1] neg_lo:[1,0,0] neg_hi:[1,0,0]
	v_mov_b32_e32 v0, v46
	v_mov_b32_e32 v1, v44
	v_pk_add_f32 v[0:1], v[170:171], v[0:1]
	v_lshlrev_b32_e32 v4, 16, v242
	v_and_b32_e32 v5, 0xffff0000, v242
	v_pk_fma_f32 v[0:1], v[6:7], v[4:5], v[0:1] op_sel_hi:[0,1,1] neg_lo:[1,0,0] neg_hi:[1,0,0]
	v_mov_b32_e32 v4, v47
	v_mov_b32_e32 v5, v45
	v_pk_add_f32 v[4:5], v[166:167], v[4:5]
	v_lshlrev_b32_e32 v2, 16, v243
	v_and_b32_e32 v3, 0xffff0000, v243
	v_pk_fma_f32 v[166:167], v[6:7], v[2:3], v[4:5] op_sel_hi:[0,1,1] neg_lo:[1,0,0] neg_hi:[1,0,0]
	v_mov_b32_e32 v175, v167
	v_mov_b32_e32 v171, v166
	v_mov_b32_e32 v174, v1
	v_mov_b32_e32 v170, v0
	v_mov_b32_e32 v169, v172
	v_mov_b32_e32 v172, v9
	v_mov_b32_e32 v168, v8
	s_cbranch_execnz .LBB0_437
	s_branch .LBB0_441
